# v39: v34 + non-temporal hint on the phase-0 weight-transpose tile loads (f32 weights are read once)
# speedup vs baseline: 1.0083x; 1.0083x over previous
.LBB0_47:
	s_and_b64 vcc, exec, s[4:5]
	s_cbranch_vccz .LBB0_49
	s_lshl_b32 s4, s46, 6
	s_add_i32 s4, s4, 0xfffe7a00
	v_or_b32_e32 v18, s4, v61
	v_lshlrev_b64 v[4:5], 2, v[18:19]
	v_lshl_add_u64 v[0:1], v[36:37], 0, v[4:5]
	global_load_dwordx4 v[0:3], v[0:1], off nt
	v_add_u32_e32 v6, v16, v63
	v_add_u32_e32 v18, s4, v70
	s_mov_b64 s[6:7], -1
	s_waitcnt vmcnt(0)
	ds_write2_b32 v6, v0, v1 offset1:1
	ds_write2_b32 v6, v2, v3 offset0:2 offset1:3
	v_lshl_add_u64 v[0:1], v[38:39], 0, v[4:5]
	global_load_dwordx4 v[0:3], v[0:1], off nt
	v_add_u32_e32 v6, v16, v65
	s_waitcnt vmcnt(0)
	ds_write2_b32 v6, v0, v1 offset1:1
	ds_write2_b32 v6, v2, v3 offset0:2 offset1:3
	v_lshl_add_u64 v[0:1], v[40:41], 0, v[4:5]
	global_load_dwordx4 v[0:3], v[0:1], off nt
	v_add_u32_e32 v6, v16, v67
	s_waitcnt vmcnt(0)
	ds_write2_b32 v6, v0, v1 offset1:1
	ds_write2_b32 v6, v2, v3 offset0:2 offset1:3
	v_lshl_add_u64 v[0:1], v[42:43], 0, v[4:5]
	global_load_dwordx4 v[0:3], v[0:1], off nt
	v_add_u32_e32 v4, v16, v69
	s_waitcnt vmcnt(0)
	ds_write2_b32 v4, v0, v1 offset1:1
	ds_write2_b32 v4, v2, v3 offset0:2 offset1:3
	s_waitcnt lgkmcnt(0)
	s_barrier
	ds_read2_b32 v[0:1], v71 offset1:65
	ds_read2_b32 v[2:3], v71 offset0:130 offset1:195
	v_add_u32_e32 v4, 0x400, v71
	s_waitcnt lgkmcnt(1)
	v_cvt_pk_bf16_f32 v0, v0, v1
	s_waitcnt lgkmcnt(0)
	v_cvt_pk_bf16_f32 v1, v2, v3
	ds_read2_b32 v[2:3], v4 offset0:4 offset1:69
	ds_read2_b32 v[4:5], v4 offset0:134 offset1:199
	s_waitcnt lgkmcnt(1)
	v_cvt_pk_bf16_f32 v2, v2, v3
	s_waitcnt lgkmcnt(0)
	v_cvt_pk_bf16_f32 v3, v4, v5
	v_lshlrev_b64 v[4:5], 7, v[18:19]
	v_lshl_add_u64 v[4:5], v[44:45], 0, v[4:5]
	global_store_dwordx4 v[4:5], v[0:3], off
	ds_read2_b32 v[0:1], v73 offset1:65
	ds_read2_b32 v[2:3], v73 offset0:130 offset1:195
	v_add_u32_e32 v4, 0x400, v73
	v_add_u32_e32 v18, s4, v72
	s_waitcnt lgkmcnt(1)
	v_cvt_pk_bf16_f32 v0, v0, v1
	s_waitcnt lgkmcnt(0)
	v_cvt_pk_bf16_f32 v1, v2, v3
	ds_read2_b32 v[2:3], v4 offset0:4 offset1:69
	ds_read2_b32 v[4:5], v4 offset0:134 offset1:199
	s_waitcnt lgkmcnt(1)
	v_cvt_pk_bf16_f32 v2, v2, v3
	s_waitcnt lgkmcnt(0)
	v_cvt_pk_bf16_f32 v3, v4, v5
	v_lshlrev_b64 v[4:5], 7, v[18:19]
	v_lshl_add_u64 v[4:5], v[44:45], 0, v[4:5]
	global_store_dwordx4 v[4:5], v[0:3], off
	s_barrier

.LBB0_50:
	s_and_b64 vcc, exec, s[4:5]
	s_cbranch_vccz .LBB0_52
	s_lshl_b32 s4, s46, 6
	s_add_i32 s4, s4, 0xfffe7c00
	v_or_b32_e32 v18, s4, v61
	v_lshlrev_b64 v[4:5], 2, v[18:19]
	v_lshl_add_u64 v[0:1], v[46:47], 0, v[4:5]
	global_load_dwordx4 v[0:3], v[0:1], off nt
	v_add_u32_e32 v6, v16, v63
	v_add_u32_e32 v18, s4, v70
	s_mov_b64 s[6:7], -1
	s_waitcnt vmcnt(0)
	ds_write2_b32 v6, v0, v1 offset1:1
	ds_write2_b32 v6, v2, v3 offset0:2 offset1:3
	v_lshl_add_u64 v[0:1], v[48:49], 0, v[4:5]
	global_load_dwordx4 v[0:3], v[0:1], off nt
	v_add_u32_e32 v6, v16, v65
	s_waitcnt vmcnt(0)
	ds_write2_b32 v6, v0, v1 offset1:1
	ds_write2_b32 v6, v2, v3 offset0:2 offset1:3
	v_lshl_add_u64 v[0:1], v[50:51], 0, v[4:5]
	global_load_dwordx4 v[0:3], v[0:1], off nt
	v_add_u32_e32 v6, v16, v67
	s_waitcnt vmcnt(0)
	ds_write2_b32 v6, v0, v1 offset1:1
	ds_write2_b32 v6, v2, v3 offset0:2 offset1:3
	v_lshl_add_u64 v[0:1], v[52:53], 0, v[4:5]
	global_load_dwordx4 v[0:3], v[0:1], off nt
	v_add_u32_e32 v4, v16, v69
	s_waitcnt vmcnt(0)
	ds_write2_b32 v4, v0, v1 offset1:1
	ds_write2_b32 v4, v2, v3 offset0:2 offset1:3
	s_waitcnt lgkmcnt(0)
	s_barrier
	ds_read2_b32 v[0:1], v71 offset1:65
	ds_read2_b32 v[2:3], v71 offset0:130 offset1:195
	v_add_u32_e32 v4, 0x400, v71
	s_waitcnt lgkmcnt(1)
	v_cvt_pk_bf16_f32 v0, v0, v1
	s_waitcnt lgkmcnt(0)
	v_cvt_pk_bf16_f32 v1, v2, v3
	ds_read2_b32 v[2:3], v4 offset0:4 offset1:69
	ds_read2_b32 v[4:5], v4 offset0:134 offset1:199
	s_waitcnt lgkmcnt(1)
	v_cvt_pk_bf16_f32 v2, v2, v3
	s_waitcnt lgkmcnt(0)
	v_cvt_pk_bf16_f32 v3, v4, v5
	v_lshlrev_b64 v[4:5], 7, v[18:19]
	v_lshl_add_u64 v[4:5], v[54:55], 0, v[4:5]
	global_store_dwordx4 v[4:5], v[0:3], off
	ds_read2_b32 v[0:1], v73 offset1:65
	ds_read2_b32 v[2:3], v73 offset0:130 offset1:195
	v_add_u32_e32 v4, 0x400, v73
	v_add_u32_e32 v18, s4, v72
	s_waitcnt lgkmcnt(1)
	v_cvt_pk_bf16_f32 v0, v0, v1
	s_waitcnt lgkmcnt(0)
	v_cvt_pk_bf16_f32 v1, v2, v3
	ds_read2_b32 v[2:3], v4 offset0:4 offset1:69
	ds_read2_b32 v[4:5], v4 offset0:134 offset1:199
	s_waitcnt lgkmcnt(1)
	v_cvt_pk_bf16_f32 v2, v2, v3
	s_waitcnt lgkmcnt(0)
	v_cvt_pk_bf16_f32 v3, v4, v5
	v_lshlrev_b64 v[4:5], 7, v[18:19]
	v_lshl_add_u64 v[4:5], v[54:55], 0, v[4:5]
	global_store_dwordx4 v[4:5], v[0:3], off
	s_barrier

.LBB0_53:
	s_and_b64 vcc, exec, s[4:5]
	s_cbranch_vccz .LBB0_57
	s_lshl_b32 s4, s46, 6
	s_and_b32 s5, s4, 0xc0
	s_lshl_b32 s4, s46, 4
	s_and_b32 s4, s4, 0x7fc0
	s_addk_i32 s4, 0x9f80
	v_mov_b32_e32 v4, 0
	s_cmp_lg_u32 s4, 0
	v_mov_b32_e32 v5, 0
	v_mov_b32_e32 v6, 0
	v_mov_b32_e32 v7, 0
	v_mov_b32_e32 v12, 0
	v_mov_b32_e32 v13, 0
	v_mov_b32_e32 v14, 0
	v_mov_b32_e32 v15, 0
	v_mov_b32_e32 v0, 0
	v_mov_b32_e32 v1, 0
	v_mov_b32_e32 v2, 0
	v_mov_b32_e32 v3, 0
	v_mov_b32_e32 v8, 0
	v_mov_b32_e32 v9, 0
	v_mov_b32_e32 v10, 0
	v_mov_b32_e32 v11, 0
	s_cbranch_scc1 .LBB0_56
	v_or_b32_e32 v0, s5, v62
	v_lshlrev_b32_e32 v18, 6, v0
	v_lshl_add_u64 v[0:1], v[18:19], 2, v[20:21]
	v_add_lshl_u32 v18, s5, v64, 6
	v_lshl_add_u64 v[2:3], v[18:19], 2, v[20:21]
	v_add_lshl_u32 v18, s5, v66, 6
	v_lshl_add_u64 v[4:5], v[18:19], 2, v[20:21]
	v_add_lshl_u32 v18, s5, v68, 6
	v_lshl_add_u64 v[6:7], v[18:19], 2, v[20:21]
	global_load_dwordx4 v[8:11], v[0:1], off nt
	s_nop 0
	global_load_dwordx4 v[0:3], v[2:3], off nt
	s_nop 0
	global_load_dwordx4 v[12:15], v[4:5], off nt
	s_nop 0
	global_load_dwordx4 v[4:7], v[6:7], off nt

.LBB0_58:
	s_and_b64 vcc, exec, s[4:5]
	s_cbranch_vccz .LBB0_62
	s_lshl_b32 s4, s46, 6
	s_and_b32 s5, s4, 0xc0
	s_lshl_b32 s4, s46, 4
	s_and_b32 s4, s4, 0x7fc0
	s_addk_i32 s4, 0xa000
	v_mov_b32_e32 v4, 0
	s_cmp_lg_u32 s4, 0
	v_mov_b32_e32 v5, 0
	v_mov_b32_e32 v6, 0
	v_mov_b32_e32 v7, 0
	v_mov_b32_e32 v12, 0
	v_mov_b32_e32 v13, 0
	v_mov_b32_e32 v14, 0
	v_mov_b32_e32 v15, 0
	v_mov_b32_e32 v0, 0
	v_mov_b32_e32 v1, 0
	v_mov_b32_e32 v2, 0
	v_mov_b32_e32 v3, 0
	v_mov_b32_e32 v8, 0
	v_mov_b32_e32 v9, 0
	v_mov_b32_e32 v10, 0
	v_mov_b32_e32 v11, 0
	s_cbranch_scc1 .LBB0_61
	v_or_b32_e32 v0, s5, v62
	v_lshlrev_b32_e32 v18, 6, v0
	v_lshl_add_u64 v[0:1], v[18:19], 2, v[24:25]
	v_add_lshl_u32 v18, s5, v64, 6
	v_lshl_add_u64 v[2:3], v[18:19], 2, v[24:25]
	v_add_lshl_u32 v18, s5, v66, 6
	v_lshl_add_u64 v[4:5], v[18:19], 2, v[24:25]
	v_add_lshl_u32 v18, s5, v68, 6
	v_lshl_add_u64 v[6:7], v[18:19], 2, v[24:25]
	global_load_dwordx4 v[8:11], v[0:1], off nt
	s_nop 0
	global_load_dwordx4 v[0:3], v[2:3], off nt
	s_nop 0
	global_load_dwordx4 v[12:15], v[4:5], off nt
	s_nop 0
	global_load_dwordx4 v[4:7], v[6:7], off nt

.LBB0_63:
	s_and_b64 vcc, exec, s[4:5]
	s_cbranch_vccz .LBB0_65
	s_lshl_b32 s4, s46, 6
	s_and_b32 s5, s4, 0x7c0
	s_lshl_b32 s4, s46, 1
	s_and_b32 s4, s4, 0xfc0
	s_addk_i32 s4, 0xf500
	v_or_b32_e32 v0, s4, v61
	v_readlane_b32 s52, v255, 13
	v_mov_b32_e32 v1, v19
	v_add_lshl_u32 v18, s5, v64, 8
	v_readlane_b32 s66, v255, 27
	v_readlane_b32 s67, v255, 28
	v_lshlrev_b64 v[4:5], 2, v[0:1]
	v_or_b32_e32 v0, s5, v62
	v_lshl_add_u64 v[2:3], v[18:19], 2, s[66:67]
	v_lshlrev_b32_e32 v18, 8, v0
	v_lshl_add_u64 v[0:1], v[18:19], 2, s[66:67]
	v_lshl_add_u64 v[0:1], v[0:1], 0, v[4:5]
	v_lshl_add_u64 v[6:7], v[2:3], 0, v[4:5]
	global_load_dwordx4 v[0:3], v[0:1], off nt
	v_add_u32_e32 v8, v16, v63
	v_add_lshl_u32 v18, s5, v68, 8
	s_lshl_b32 s30, s5, 1
	v_readlane_b32 s53, v255, 14
	v_readlane_b32 s54, v255, 15
	v_readlane_b32 s55, v255, 16
	v_readlane_b32 s56, v255, 17
	v_readlane_b32 s57, v255, 18
	v_readlane_b32 s58, v255, 19
	v_readlane_b32 s59, v255, 20
	v_readlane_b32 s60, v255, 21
	v_readlane_b32 s61, v255, 22
	v_readlane_b32 s62, v255, 23
	v_readlane_b32 s63, v255, 24
	v_readlane_b32 s64, v255, 25
	v_readlane_b32 s65, v255, 26
	s_waitcnt vmcnt(0)
	ds_write2_b32 v8, v0, v1 offset1:1
	ds_write2_b32 v8, v2, v3 offset0:2 offset1:3
	global_load_dwordx4 v[0:3], v[6:7], off nt
	v_add_u32_e32 v6, v16, v65
	s_waitcnt vmcnt(0)
	ds_write2_b32 v6, v0, v1 offset1:1
	ds_write2_b32 v6, v2, v3 offset0:2 offset1:3
	v_lshl_add_u64 v[0:1], v[18:19], 2, s[66:67]
	v_add_lshl_u32 v18, s5, v66, 8
	v_lshl_add_u64 v[6:7], v[0:1], 0, v[4:5]
	v_lshl_add_u64 v[0:1], v[18:19], 2, s[66:67]
	v_lshl_add_u64 v[0:1], v[0:1], 0, v[4:5]
	global_load_dwordx4 v[0:3], v[0:1], off nt
	v_add_u32_e32 v4, v16, v67
	s_waitcnt vmcnt(0)
	ds_write2_b32 v4, v0, v1 offset1:1
	ds_write2_b32 v4, v2, v3 offset0:2 offset1:3
	global_load_dwordx4 v[0:3], v[6:7], off nt
	v_add_u32_e32 v4, v16, v69
	v_add_u32_e32 v6, 0x400, v71
	s_waitcnt vmcnt(0)
	ds_write2_b32 v4, v0, v1 offset1:1
	ds_write2_b32 v4, v2, v3 offset0:2 offset1:3
	s_waitcnt lgkmcnt(0)
	s_barrier
	ds_read2_b32 v[0:1], v71 offset1:65
	ds_read2_b32 v[2:3], v71 offset0:130 offset1:195
	v_lshl_add_u64 v[4:5], v[28:29], 0, s[30:31]
	s_waitcnt lgkmcnt(1)
	v_cvt_pk_bf16_f32 v0, v0, v1
	s_waitcnt lgkmcnt(0)
	v_cvt_pk_bf16_f32 v1, v2, v3
	ds_read2_b32 v[2:3], v6 offset0:4 offset1:69
	ds_read2_b32 v[6:7], v6 offset0:134 offset1:199
	s_waitcnt lgkmcnt(1)
	v_cvt_pk_bf16_f32 v2, v2, v3
	s_waitcnt lgkmcnt(0)
	v_cvt_pk_bf16_f32 v3, v6, v7
	v_add_u32_e32 v6, s4, v70
	v_mad_u64_u32 v[6:7], s[6:7], v6, s42, v[4:5]
	global_store_dwordx4 v[6:7], v[0:3], off
	ds_read2_b32 v[0:1], v73 offset1:65
	ds_read2_b32 v[2:3], v73 offset0:130 offset1:195
	v_add_u32_e32 v6, 0x400, v73
	s_mov_b64 s[6:7], -1
	s_waitcnt lgkmcnt(1)
	v_cvt_pk_bf16_f32 v0, v0, v1
	s_waitcnt lgkmcnt(0)
	v_cvt_pk_bf16_f32 v1, v2, v3
	ds_read2_b32 v[2:3], v6 offset0:4 offset1:69
	ds_read2_b32 v[6:7], v6 offset0:134 offset1:199
	s_waitcnt lgkmcnt(1)
	v_cvt_pk_bf16_f32 v2, v2, v3
	s_waitcnt lgkmcnt(0)
	v_cvt_pk_bf16_f32 v3, v6, v7
	v_add_u32_e32 v6, s4, v72
	v_mad_u64_u32 v[4:5], s[4:5], v6, s42, v[4:5]
	global_store_dwordx4 v[4:5], v[0:3], off
	s_barrier

.LBB0_66:
	s_and_b64 vcc, exec, s[4:5]
	s_cbranch_vccz .LBB0_68
	s_lshl_b32 s4, s46, 6
	s_and_b32 s5, s4, 0x7c0
	s_lshl_b32 s4, s46, 1
	s_and_b32 s4, s4, 0xfc0
	s_addk_i32 s4, 0xf600
	v_or_b32_e32 v0, s4, v61
	v_readlane_b32 s52, v255, 13
	v_mov_b32_e32 v1, v19
	v_add_lshl_u32 v18, s5, v64, 8
	v_readlane_b32 s60, v255, 21
	v_readlane_b32 s61, v255, 22
	v_lshlrev_b64 v[4:5], 2, v[0:1]
	v_or_b32_e32 v0, s5, v62
	v_lshl_add_u64 v[2:3], v[18:19], 2, s[60:61]
	v_lshlrev_b32_e32 v18, 8, v0
	v_lshl_add_u64 v[0:1], v[18:19], 2, s[60:61]
	v_lshl_add_u64 v[0:1], v[0:1], 0, v[4:5]
	v_lshl_add_u64 v[6:7], v[2:3], 0, v[4:5]
	global_load_dwordx4 v[0:3], v[0:1], off nt
	v_add_u32_e32 v8, v16, v63
	v_add_lshl_u32 v18, s5, v68, 8
	s_lshl_b32 s30, s5, 1
	v_readlane_b32 s53, v255, 14
	v_readlane_b32 s54, v255, 15
	v_readlane_b32 s55, v255, 16
	v_readlane_b32 s56, v255, 17
	v_readlane_b32 s57, v255, 18
	v_readlane_b32 s58, v255, 19
	v_readlane_b32 s59, v255, 20
	v_readlane_b32 s62, v255, 23
	v_readlane_b32 s63, v255, 24
	v_readlane_b32 s64, v255, 25
	v_readlane_b32 s65, v255, 26
	v_readlane_b32 s66, v255, 27
	v_readlane_b32 s67, v255, 28
	s_waitcnt vmcnt(0)
	ds_write2_b32 v8, v0, v1 offset1:1
	ds_write2_b32 v8, v2, v3 offset0:2 offset1:3
	global_load_dwordx4 v[0:3], v[6:7], off nt
	v_add_u32_e32 v6, v16, v65
	s_waitcnt vmcnt(0)
	ds_write2_b32 v6, v0, v1 offset1:1
	ds_write2_b32 v6, v2, v3 offset0:2 offset1:3
	v_lshl_add_u64 v[0:1], v[18:19], 2, s[60:61]
	v_add_lshl_u32 v18, s5, v66, 8
	v_lshl_add_u64 v[6:7], v[0:1], 0, v[4:5]
	v_lshl_add_u64 v[0:1], v[18:19], 2, s[60:61]
	v_lshl_add_u64 v[0:1], v[0:1], 0, v[4:5]
	global_load_dwordx4 v[0:3], v[0:1], off nt
	v_add_u32_e32 v4, v16, v67
	s_waitcnt vmcnt(0)
	ds_write2_b32 v4, v0, v1 offset1:1
	ds_write2_b32 v4, v2, v3 offset0:2 offset1:3
	global_load_dwordx4 v[0:3], v[6:7], off nt
	v_add_u32_e32 v4, v16, v69
	v_add_u32_e32 v6, 0x400, v71
	s_waitcnt vmcnt(0)
	ds_write2_b32 v4, v0, v1 offset1:1
	ds_write2_b32 v4, v2, v3 offset0:2 offset1:3
	s_waitcnt lgkmcnt(0)
	s_barrier
	ds_read2_b32 v[0:1], v71 offset1:65
	ds_read2_b32 v[2:3], v71 offset0:130 offset1:195
	v_lshl_add_u64 v[4:5], v[30:31], 0, s[30:31]
	s_waitcnt lgkmcnt(1)
	v_cvt_pk_bf16_f32 v0, v0, v1
	s_waitcnt lgkmcnt(0)
	v_cvt_pk_bf16_f32 v1, v2, v3
	ds_read2_b32 v[2:3], v6 offset0:4 offset1:69
	ds_read2_b32 v[6:7], v6 offset0:134 offset1:199
	s_waitcnt lgkmcnt(1)
	v_cvt_pk_bf16_f32 v2, v2, v3
	s_waitcnt lgkmcnt(0)
	v_cvt_pk_bf16_f32 v3, v6, v7
	v_add_u32_e32 v6, s4, v70
	v_mad_u64_u32 v[6:7], s[6:7], v6, s42, v[4:5]
	global_store_dwordx4 v[6:7], v[0:3], off
	ds_read2_b32 v[0:1], v73 offset1:65
	ds_read2_b32 v[2:3], v73 offset0:130 offset1:195
	v_add_u32_e32 v6, 0x400, v73
	s_mov_b64 s[6:7], -1
	s_waitcnt lgkmcnt(1)
	v_cvt_pk_bf16_f32 v0, v0, v1
	s_waitcnt lgkmcnt(0)
	v_cvt_pk_bf16_f32 v1, v2, v3
	ds_read2_b32 v[2:3], v6 offset0:4 offset1:69
	ds_read2_b32 v[6:7], v6 offset0:134 offset1:199
	s_waitcnt lgkmcnt(1)
	v_cvt_pk_bf16_f32 v2, v2, v3
	s_waitcnt lgkmcnt(0)
	v_cvt_pk_bf16_f32 v3, v6, v7
	v_add_u32_e32 v6, s4, v72
	v_mad_u64_u32 v[4:5], s[4:5], v6, s42, v[4:5]
	global_store_dwordx4 v[4:5], v[0:3], off
	s_barrier

.LBB0_69:
	s_and_b64 vcc, exec, s[4:5]
	s_cbranch_vccz .LBB0_71
	s_lshl_b32 s4, s46, 6
	s_and_b32 s5, s4, 0x3c0
	s_lshl_b32 s4, s46, 2
	s_and_b32 s4, s4, 0x1fc0
	s_addk_i32 s4, 0xf000
	v_or_b32_e32 v0, s4, v61
	v_readlane_b32 s48, v255, 45
	v_mov_b32_e32 v1, v19
	v_add_lshl_u32 v18, s5, v64, 10
	v_readlane_b32 s54, v255, 51
	v_readlane_b32 s55, v255, 52
	v_lshlrev_b64 v[4:5], 2, v[0:1]
	v_or_b32_e32 v0, s5, v62
	v_lshl_add_u64 v[2:3], v[18:19], 2, s[54:55]
	v_lshlrev_b32_e32 v18, 10, v0
	v_lshl_add_u64 v[0:1], v[18:19], 2, s[54:55]
	v_lshl_add_u64 v[0:1], v[0:1], 0, v[4:5]
	v_lshl_add_u64 v[6:7], v[2:3], 0, v[4:5]
	global_load_dwordx4 v[0:3], v[0:1], off nt
	v_add_u32_e32 v8, v16, v63
	v_add_lshl_u32 v18, s5, v68, 10
	s_lshl_b32 s30, s5, 1
	v_readlane_b32 s49, v255, 46
	v_readlane_b32 s50, v255, 47
	v_readlane_b32 s51, v255, 48
	v_readlane_b32 s52, v255, 49
	v_readlane_b32 s53, v255, 50
	v_readlane_b32 s56, v255, 53
	v_readlane_b32 s57, v255, 54
	v_readlane_b32 s58, v255, 55
	v_readlane_b32 s59, v255, 56
	v_readlane_b32 s60, v255, 57
	v_readlane_b32 s61, v255, 58
	v_readlane_b32 s62, v255, 59
	v_readlane_b32 s63, v255, 60
	s_waitcnt vmcnt(0)
	ds_write2_b32 v8, v0, v1 offset1:1
	ds_write2_b32 v8, v2, v3 offset0:2 offset1:3
	global_load_dwordx4 v[0:3], v[6:7], off nt
	v_add_u32_e32 v6, v16, v65
	s_waitcnt vmcnt(0)
	ds_write2_b32 v6, v0, v1 offset1:1
	ds_write2_b32 v6, v2, v3 offset0:2 offset1:3
	v_lshl_add_u64 v[0:1], v[18:19], 2, s[54:55]
	v_add_lshl_u32 v18, s5, v66, 10
	v_lshl_add_u64 v[6:7], v[0:1], 0, v[4:5]
	v_lshl_add_u64 v[0:1], v[18:19], 2, s[54:55]
	v_lshl_add_u64 v[0:1], v[0:1], 0, v[4:5]
	global_load_dwordx4 v[0:3], v[0:1], off nt
	v_add_u32_e32 v4, v16, v67
	s_waitcnt vmcnt(0)
	ds_write2_b32 v4, v0, v1 offset1:1
	ds_write2_b32 v4, v2, v3 offset0:2 offset1:3
	global_load_dwordx4 v[0:3], v[6:7], off nt
	v_add_u32_e32 v4, v16, v69
	v_add_u32_e32 v6, 0x400, v71
	s_waitcnt vmcnt(0)
	ds_write2_b32 v4, v0, v1 offset1:1
	ds_write2_b32 v4, v2, v3 offset0:2 offset1:3
	s_waitcnt lgkmcnt(0)
	s_barrier
	ds_read2_b32 v[0:1], v71 offset1:65
	ds_read2_b32 v[2:3], v71 offset0:130 offset1:195
	v_lshl_add_u64 v[4:5], v[32:33], 0, s[30:31]
	s_waitcnt lgkmcnt(1)
	v_cvt_pk_bf16_f32 v0, v0, v1
	s_waitcnt lgkmcnt(0)
	v_cvt_pk_bf16_f32 v1, v2, v3
	ds_read2_b32 v[2:3], v6 offset0:4 offset1:69
	ds_read2_b32 v[6:7], v6 offset0:134 offset1:199
	s_waitcnt lgkmcnt(1)
	v_cvt_pk_bf16_f32 v2, v2, v3
	s_waitcnt lgkmcnt(0)
	v_cvt_pk_bf16_f32 v3, v6, v7
	v_add_u32_e32 v6, s4, v70
	v_mad_u64_u32 v[6:7], s[6:7], v6, s43, v[4:5]
	global_store_dwordx4 v[6:7], v[0:3], off
	ds_read2_b32 v[0:1], v73 offset1:65
	ds_read2_b32 v[2:3], v73 offset0:130 offset1:195
	v_add_u32_e32 v6, 0x400, v73
	s_mov_b64 s[6:7], -1
	s_waitcnt lgkmcnt(1)
	v_cvt_pk_bf16_f32 v0, v0, v1
	s_waitcnt lgkmcnt(0)
	v_cvt_pk_bf16_f32 v1, v2, v3
	ds_read2_b32 v[2:3], v6 offset0:4 offset1:69
	ds_read2_b32 v[6:7], v6 offset0:134 offset1:199
	s_waitcnt lgkmcnt(1)
	v_cvt_pk_bf16_f32 v2, v2, v3
	s_waitcnt lgkmcnt(0)
	v_cvt_pk_bf16_f32 v3, v6, v7
	v_add_u32_e32 v6, s4, v72
	v_mad_u64_u32 v[4:5], s[4:5], v6, s43, v[4:5]
	global_store_dwordx4 v[4:5], v[0:3], off
	s_barrier

.LBB0_74:
	s_or_saveexec_b64 s[10:11], s[4:5]
	s_lshl_b32 s4, s46, 6
	v_cndmask_b32_e64 v0, 0, 1, s[28:29]
	s_and_b32 s30, s4, 0x3c0
	v_mov_b32_e32 v3, 0
	v_cmp_ne_u32_e64 s[4:5], 1, v0
	v_mov_b32_e32 v2, 0
	v_mov_b32_e32 v1, 0
	v_mov_b32_e32 v0, 0
	s_xor_b64 exec, exec, s[10:11]
	s_cbranch_execz .LBB0_79
	v_or_b32_e32 v5, s30, v62
	v_readlane_b32 s52, v255, 13
	v_mul_u32_u24_e32 v0, 0xf98, v5
	v_mov_b32_e32 v1, v19
	v_readlane_b32 s56, v255, 17
	v_readlane_b32 s57, v255, 18
	v_readlane_b32 s54, v255, 15
	v_readlane_b32 s55, v255, 16
	v_lshl_add_u64 v[0:1], v[0:1], 2, s[56:57]
	v_lshl_add_u64 v[0:1], v[18:19], 2, v[0:1]
	global_load_dwordx4 v[0:3], v[0:1], off nt
	s_and_b64 vcc, exec, s[4:5]
	v_readlane_b32 s53, v255, 14
	v_readlane_b32 s58, v255, 19
	v_readlane_b32 s59, v255, 20
	v_readlane_b32 s60, v255, 21
	v_readlane_b32 s61, v255, 22
	v_readlane_b32 s62, v255, 23
	v_readlane_b32 s63, v255, 24
	v_readlane_b32 s64, v255, 25
	v_readlane_b32 s65, v255, 26
	v_readlane_b32 s66, v255, 27
	v_readlane_b32 s67, v255, 28
	s_cbranch_vccnz .LBB0_77
	v_lshlrev_b32_e32 v5, 2, v5
	global_load_dword v6, v5, s[54:55]
	s_waitcnt vmcnt(0)
	v_pk_mul_f32 v[0:1], v[0:1], v[6:7] op_sel_hi:[1,0]
	v_pk_mul_f32 v[2:3], v[2:3], v[6:7] op_sel_hi:[1,0]
.LBB0_77:
	s_waitcnt vmcnt(0)
	ds_write2_b32 v4, v0, v1 offset1:1
	ds_write2_b32 v4, v2, v3 offset0:2 offset1:3
	v_add_u32_e32 v4, s30, v64
	v_mul_u32_u24_e32 v0, 0xf98, v4
	v_mov_b32_e32 v1, v19
	v_lshl_add_u64 v[0:1], v[0:1], 2, s[56:57]
	v_lshl_add_u64 v[0:1], v[18:19], 2, v[0:1]
	global_load_dwordx4 v[0:3], v[0:1], off nt
	s_and_b64 vcc, exec, s[4:5]
	s_cbranch_vccnz .LBB0_79
	v_lshlrev_b32_e32 v4, 2, v4
	global_load_dword v4, v4, s[54:55]
	s_waitcnt vmcnt(0)
	v_pk_mul_f32 v[0:1], v[0:1], v[4:5] op_sel_hi:[1,0]
	v_pk_mul_f32 v[2:3], v[2:3], v[4:5] op_sel_hi:[1,0]

.LBB0_81:
	s_or_saveexec_b64 s[6:7], s[6:7]
	v_mov_b32_e32 v3, 0
	v_mov_b32_e32 v2, 0
	v_mov_b32_e32 v1, 0
	v_mov_b32_e32 v0, 0
	s_xor_b64 exec, exec, s[6:7]
	s_cbranch_execz .LBB0_86
	v_add_u32_e32 v5, s30, v66
	v_readlane_b32 s52, v255, 13
	v_mul_u32_u24_e32 v0, 0xf98, v5
	v_mov_b32_e32 v1, v19
	v_readlane_b32 s56, v255, 17
	v_readlane_b32 s57, v255, 18
	v_readlane_b32 s54, v255, 15
	v_readlane_b32 s55, v255, 16
	v_lshl_add_u64 v[0:1], v[0:1], 2, s[56:57]
	v_lshl_add_u64 v[0:1], v[18:19], 2, v[0:1]
	global_load_dwordx4 v[0:3], v[0:1], off nt
	s_and_b64 vcc, exec, s[4:5]
	v_readlane_b32 s53, v255, 14
	v_readlane_b32 s58, v255, 19
	v_readlane_b32 s59, v255, 20
	v_readlane_b32 s60, v255, 21
	v_readlane_b32 s61, v255, 22
	v_readlane_b32 s62, v255, 23
	v_readlane_b32 s63, v255, 24
	v_readlane_b32 s64, v255, 25
	v_readlane_b32 s65, v255, 26
	v_readlane_b32 s66, v255, 27
	v_readlane_b32 s67, v255, 28
	s_cbranch_vccnz .LBB0_84
	v_lshlrev_b32_e32 v5, 2, v5
	global_load_dword v6, v5, s[54:55]
	s_waitcnt vmcnt(0)
	v_pk_mul_f32 v[0:1], v[0:1], v[6:7] op_sel_hi:[1,0]
	v_pk_mul_f32 v[2:3], v[2:3], v[6:7] op_sel_hi:[1,0]
.LBB0_84:
	s_waitcnt vmcnt(0)
	ds_write2_b32 v4, v0, v1 offset1:1
	ds_write2_b32 v4, v2, v3 offset0:2 offset1:3
	v_add_u32_e32 v4, s30, v68
	v_mul_u32_u24_e32 v0, 0xf98, v4
	v_mov_b32_e32 v1, v19
	v_lshl_add_u64 v[0:1], v[0:1], 2, s[56:57]
	v_lshl_add_u64 v[0:1], v[18:19], 2, v[0:1]
	global_load_dwordx4 v[0:3], v[0:1], off nt
	s_and_b64 vcc, exec, s[4:5]
	s_cbranch_vccnz .LBB0_86
	v_lshlrev_b32_e32 v4, 2, v4
	global_load_dword v4, v4, s[54:55]
	s_waitcnt vmcnt(0)
	v_pk_mul_f32 v[0:1], v[0:1], v[4:5] op_sel_hi:[1,0]
	v_pk_mul_f32 v[2:3], v[2:3], v[4:5] op_sel_hi:[1,0]
